# adds: DPP (quad_perm/row_mirror) steps replace 4 of 5 ds_swizzle steps in row_post wave sums (bit-identical)
# speedup vs baseline: 1.0209x; 1.0015x over previous
; __device__ __forceinline__ float bflo(unsigned w) { return __uint_as_float(w << 16); }
; __device__ __forceinline__ float bfhi(unsigned w) { return __uint_as_float(w & 0xffff0000u); }
; __device__ __forceinline__ unsigned pk2(float lo, float hi) { const f32x2 v = {lo, hi}; return __builtin_bit_cast(unsigned, __builtin_convertvector(v, bf16x2_t)); }
; template <int K> __device__ __forceinline__ float swz_xor(float v) { return __int_as_float(__builtin_amdgcn_ds_swizzle(__float_as_int(v), (K << 10) | 0x1f)); }
; __device__ __forceinline__ float half_sum(float v) { auto rr = __builtin_amdgcn_permlane32_swap(__float_as_uint(v), __float_as_uint(v), false, false); return __uint_as_float(rr[0]) + __uint_as_float(rr[1]); }
; __device__ __forceinline__ float wave_sum(float v) { v += swz_xor<1>(v); v += swz_xor<2>(v); v += swz_xor<4>(v); v += swz_xor<8>(v); v += swz_xor<16>(v); return half_sum(v); }
; __device__ __forceinline__ void row_post(bf16* Z, bf16* CQN, bf16* CKV, bf16* KR, float* out, const float* qg, const float* kvg, int r, int lane) {
;     bf16* z = Z + (size_t)r * NZ; const float pos = (float)row_pos(r);
;     { const u32x2 raw = *(const u32x2*)(z + 4 * lane); const float v0 = bflo(raw.x), v1 = bfhi(raw.x), v2 = bflo(raw.y), v3 = bfhi(raw.y);
;       const float rstd = rsqrtf(wave_sum((v0 * v0 + v1 * v1) + (v2 * v2 + v3 * v3)) * (1.f / 256.f) + EPS); const f32x4 g = *(const f32x4*)(qg + 4 * lane);
;       u32x2 w; w.x = pk2(v0 * rstd * g.x, v1 * rstd * g.y); w.y = pk2(v2 * rstd * g.z, v3 * rstd * g.w); *(u32x2*)(CQN + (size_t)r * 256 + 4 * lane) = w; }
;     { const unsigned raw = *(const unsigned*)(z + ZC_CKV + 2 * lane); const float v0 = bflo(raw), v1 = bfhi(raw);
;       const float rstd = rsqrtf(wave_sum(v0 * v0 + v1 * v1) * (1.f / 128.f) + EPS); const f32x2 g = *(const f32x2*)(kvg + 2 * lane);
;       const float y0 = v0 * rstd * g.x, y1 = v1 * rstd * g.y;
;       float* o = (r < MP ? out + O_PCKV + (size_t)r * 128 : out + O_SCKV + (size_t)(r - MP) * 128) + 2 * lane; *(f32x2*)o = (f32x2){y0, y1};
;       if (r < MP) *(unsigned*)(CKV + (size_t)r * 128 + 2 * lane) = pk2(y0, y1); }
.LBB0_321:
	v_lshl_add_u64 v[32:33], v[30:31], 0, s[14:15]
	global_load_dwordx2 v[46:47], v[32:33], off
	global_load_dwordx4 v[42:45], v[2:3], off
	v_lshl_add_u64 v[66:67], v[28:29], 0, s[14:15]
	global_load_dword v68, v[66:67], off
	global_load_dwordx2 v[70:71], v[4:5], off
	s_mov_b64 s[98:99], 0x6800000
	v_lshl_add_u64 v[72:73], v[26:27], 0, s[14:15]
	v_lshl_add_u64 v[72:73], v[72:73], 0, s[98:99]
	s_and_saveexec_b64 s[100:101], s[2:3]
	global_load_ushort v74, v[72:73], off offset:768
	global_load_ushort v75, v[72:73], off offset:800
	s_mov_b64 exec, s[100:101]
	global_load_ushort v76, v[72:73], off offset:832
	global_load_ushort v77, v[72:73], off offset:960
	global_load_ushort v78, v[72:73], off offset:1856
	global_load_ushort v79, v[72:73], off offset:1984
	global_load_ushort v80, v[72:73], off offset:1088
	global_load_ushort v81, v[72:73], off offset:1216
	global_load_ushort v82, v[72:73], off offset:2112
	global_load_ushort v83, v[72:73], off offset:2240
	global_load_ushort v84, v[72:73], off offset:1344
	global_load_ushort v85, v[72:73], off offset:1472
	global_load_ushort v86, v[72:73], off offset:2368
	global_load_ushort v87, v[72:73], off offset:2496
	global_load_ushort v88, v[72:73], off offset:1600
	global_load_ushort v89, v[72:73], off offset:1728
	global_load_ushort v90, v[72:73], off offset:2624
	global_load_ushort v91, v[72:73], off offset:2752
	s_add_i32 s35, s8, s12
	s_cmp_lt_i32 s35, 0x8000
	s_cselect_b64 s[16:17], -1, 0
	s_add_u32 s36, s28, s10
	s_addc_u32 s37, s29, s11
	s_add_u32 s38, s31, s10
	s_addc_u32 s39, s34, s11
	s_and_b64 s[18:19], s[16:17], exec
	s_cselect_b32 s18, s36, s38
	s_cselect_b32 s19, s37, s39
	s_cmpk_gt_i32 s35, 0x7fff
	s_waitcnt vmcnt(18) lgkmcnt(0)
	v_lshlrev_b32_e32 v32, 16, v47
	v_and_b32_e32 v33, 0xffff0000, v47
	v_lshlrev_b32_e32 v48, 16, v46
	v_and_b32_e32 v49, 0xffff0000, v46
	v_pk_mul_f32 v[46:47], v[32:33], v[32:33]
	v_pk_mul_f32 v[50:51], v[48:49], v[48:49]
	v_add_f32_e32 v41, v46, v47
	v_add_f32_e32 v46, v50, v51
	v_add_f32_e32 v41, v46, v41
	v_lshl_add_u64 v[50:51], v[28:29], 0, s[14:15]
	s_nop 1
	v_add_f32_dpp v41, v41, v41 quad_perm:[1,0,3,2] row_mask:0xf bank_mask:0xf
	s_nop 1
	v_add_f32_dpp v41, v41, v41 quad_perm:[2,3,0,1] row_mask:0xf bank_mask:0xf
	s_nop 1
	v_add_f32_dpp v41, v41, v41 row_half_mirror row_mask:0xf bank_mask:0xf
	s_nop 1
	v_add_f32_dpp v41, v41, v41 row_mirror row_mask:0xf bank_mask:0xf
	ds_swizzle_b32 v46, v41 offset:swizzle(SWAP,16)
	s_waitcnt lgkmcnt(0)
	v_add_f32_e32 v41, v41, v46
	v_mov_b32_e32 v46, v41
	s_nop 1
	v_permlane32_swap_b32_e32 v41, v46
	v_add_f32_e32 v41, v41, v46
	v_fmamk_f32 v41, v41, 0x3b800000, v39
	v_mul_f32_e32 v46, 0x4b800000, v41
	v_cmp_gt_f32_e32 vcc, s26, v41
	s_nop 1
	v_cndmask_b32_e32 v41, v41, v46, vcc
	v_rsq_f32_e32 v41, v41
	v_lshl_add_u64 v[46:47], v[24:25], 0, s[10:11]
	v_mul_f32_e32 v52, 0x45800000, v41
	v_cndmask_b32_e32 v52, v41, v52, vcc
	v_pk_mul_f32 v[48:49], v[52:53], v[48:49] op_sel_hi:[0,1]
	v_pk_mul_f32 v[32:33], v[52:53], v[32:33] op_sel_hi:[0,1]
	v_pk_mul_f32 v[42:43], v[42:43], v[48:49]
	v_pk_mul_f32 v[32:33], v[44:45], v[32:33]
	v_cvt_pk_bf16_f32 v42, v42, v43
	v_cvt_pk_bf16_f32 v43, v32, v33
	global_store_dwordx2 v[46:47], v[42:43], off
	s_waitcnt vmcnt(17) lgkmcnt(0)
	v_mov_b32_e32 v41, v68
	v_mov_b64_e32 v[32:33], v[70:71]
	v_lshlrev_b32_e32 v42, 16, v41
	v_and_b32_e32 v43, 0xffff0000, v41
	v_pk_mul_f32 v[44:45], v[42:43], v[42:43]
	s_nop 0
	v_add_f32_e32 v41, v44, v45
	s_nop 1
	v_add_f32_dpp v41, v41, v41 quad_perm:[1,0,3,2] row_mask:0xf bank_mask:0xf
	s_nop 1
	v_add_f32_dpp v41, v41, v41 quad_perm:[2,3,0,1] row_mask:0xf bank_mask:0xf
	s_nop 1
	v_add_f32_dpp v41, v41, v41 row_half_mirror row_mask:0xf bank_mask:0xf
	s_nop 1
	v_add_f32_dpp v41, v41, v41 row_mirror row_mask:0xf bank_mask:0xf
	ds_swizzle_b32 v44, v41 offset:swizzle(SWAP,16)
	s_waitcnt lgkmcnt(0)
	v_add_f32_e32 v41, v41, v44
	v_mov_b32_e32 v44, v41
	s_nop 1
	v_permlane32_swap_b32_e32 v41, v44
	v_add_f32_e32 v41, v41, v44
	v_fmamk_f32 v41, v41, 0x3c000000, v39
	v_mul_f32_e32 v44, 0x4b800000, v41
	v_cmp_gt_f32_e32 vcc, s26, v41
	s_nop 1
	v_cndmask_b32_e32 v41, v41, v44, vcc
	v_rsq_f32_e32 v41, v41
	s_nop 0
	v_mul_f32_e32 v44, 0x45800000, v41
	v_cndmask_b32_e32 v44, v41, v44, vcc
	v_pk_mul_f32 v[42:43], v[44:45], v[42:43] op_sel_hi:[0,1]
	v_pk_mul_f32 v[32:33], v[32:33], v[42:43]
	v_lshl_add_u64 v[42:43], s[18:19], 0, v[18:19]
	global_store_dwordx2 v[42:43], v[32:33], off
	s_cbranch_scc1 .LBB0_323
	v_cvt_pk_bf16_f32 v32, v32, v33
	global_store_dword v[20:21], v32, off
